# ff1 GEMM epilogue: the eight per-chunk row-statistic loads of a tile are issued together up front; later chunks no longer wait (vmcnt(0)) behind the previous chunk's stores
# speedup vs baseline: 1.0114x; 1.0051x over previous
.LBB0_756:
	v_lshl_add_u32 v164, s4, 8, v168
	v_ashrrev_i32_e32 v165, 31, v164
	v_lshl_add_u64 v[160:161], v[164:165], 2, s[12:13]
	global_load_dword v177, v[160:161], off
	global_load_dword v230, v[160:161], off offset:64
	global_load_dword v231, v[160:161], off offset:128
	global_load_dword v232, v[160:161], off offset:192
	global_load_dword v233, v[160:161], off offset:512
	global_load_dword v234, v[160:161], off offset:576
	global_load_dword v235, v[160:161], off offset:640
	global_load_dword v236, v[160:161], off offset:704
	s_ashr_i32 s4, s4, 4
	s_ashr_i32 s5, s4, 31
	s_lshl_b64 s[4:5], s[4:5], 14
	v_lshl_or_b32 v162, s3, 8, v170
	s_add_u32 s4, s67, s4
	v_ashrrev_i32_e32 v163, 31, v162
	s_addc_u32 s5, s68, s5
	v_lshl_add_u64 v[88:89], v[162:163], 2, s[4:5]
	global_load_dwordx4 v[100:103], v[88:89], off
	global_load_dwordx4 v[96:99], v[88:89], off offset:16
	global_load_dwordx4 v[92:95], v[88:89], off offset:512
	s_nop 0
	global_load_dwordx4 v[88:91], v[88:89], off offset:528
	v_lshlrev_b64 v[166:167], 1, v[162:163]
	v_lshlrev_b64 v[178:179], 13, v[164:165]
	v_or_b32_e32 v176, 16, v164
	s_waitcnt vmcnt(0)
	v_fmamk_f32 v162, v177, 0x3a800000, v174
	v_mul_f32_e32 v163, 0x4f800000, v162
	v_cmp_gt_f32_e32 vcc, s75, v162
	v_ashrrev_i32_e32 v177, 31, v176
	s_nop 0
	v_cndmask_b32_e32 v165, v162, v163, vcc
	v_sqrt_f32_e32 v180, v165
	v_lshl_add_u64 v[162:163], s[22:23], 0, v[178:179]
	v_lshl_add_u64 v[162:163], v[162:163], 0, v[166:167]
	v_lshl_add_u64 v[178:179], v[176:177], 2, s[12:13]
	v_add_u32_e32 v181, -1, v180
	v_add_u32_e32 v182, 1, v180
	v_fma_f32 v183, -v181, v180, v165
	v_fma_f32 v184, -v182, v180, v165
	v_cmp_ge_f32_e64 s[4:5], 0, v183
	s_nop 1
	v_cndmask_b32_e64 v180, v180, v181, s[4:5]
	v_cmp_lt_f32_e64 s[4:5], 0, v184
	s_nop 1
	v_cndmask_b32_e64 v180, v180, v182, s[4:5]
	v_mul_f32_e32 v181, 0x37800000, v180
	v_cndmask_b32_e32 v180, v180, v181, vcc
	v_cmp_class_f32_e32 vcc, v165, v175
	s_nop 1
	v_cndmask_b32_e32 v165, v180, v165, vcc
	v_div_scale_f32 v180, s[4:5], v165, v165, 1.0
	v_rcp_f32_e32 v181, v180
	v_div_scale_f32 v182, vcc, 1.0, v165, 1.0
	v_fma_f32 v183, -v180, v181, 1.0
	v_fmac_f32_e32 v181, v183, v181
	v_mul_f32_e32 v183, v182, v181
	v_fma_f32 v184, -v180, v183, v182
	v_fmac_f32_e32 v183, v184, v181
	v_fma_f32 v180, -v180, v183, v182
	v_div_fmas_f32 v180, v180, v181, v183
	v_div_fixup_f32 v180, v180, v165, 1.0
	v_pk_fma_f32 v[142:143], v[142:143], v[180:181], v[102:103] op_sel_hi:[1,0,1]
	v_pk_fma_f32 v[140:141], v[140:141], v[180:181], v[100:101] op_sel_hi:[1,0,1]
	v_pk_fma_f32 v[138:139], v[138:139], v[180:181], v[98:99] op_sel_hi:[1,0,1]
	v_pk_fma_f32 v[136:137], v[136:137], v[180:181], v[96:97] op_sel_hi:[1,0,1]
	v_pk_fma_f32 v[134:135], v[134:135], v[180:181], v[94:95] op_sel_hi:[1,0,1]
	v_pk_fma_f32 v[132:133], v[132:133], v[180:181], v[92:93] op_sel_hi:[1,0,1]
	v_pk_fma_f32 v[130:131], v[130:131], v[180:181], v[90:91] op_sel_hi:[1,0,1]
	v_pk_fma_f32 v[128:129], v[128:129], v[180:181], v[88:89] op_sel_hi:[1,0,1]
	v_max_f32_e32 v140, 0, v140
	v_max_f32_e32 v136, 0, v136
	v_max_f32_e32 v141, 0, v141
	v_max_f32_e32 v137, 0, v137
	v_max_f32_e32 v142, 0, v142
	v_max_f32_e32 v138, 0, v138
	v_max_f32_e32 v143, 0, v143
	v_max_f32_e32 v139, 0, v139
	v_max_f32_e32 v132, 0, v132
	v_max_f32_e32 v128, 0, v128
	v_max_f32_e32 v133, 0, v133
	v_max_f32_e32 v129, 0, v129
	v_max_f32_e32 v134, 0, v134
	v_max_f32_e32 v130, 0, v130
	v_max_f32_e32 v135, 0, v135
	v_max_f32_e32 v131, 0, v131
	v_pk_mul_f32 v[140:141], v[140:141], v[140:141]
	v_pk_mul_f32 v[136:137], v[136:137], v[136:137]
	v_pk_mul_f32 v[142:143], v[142:143], v[142:143]
	v_pk_mul_f32 v[138:139], v[138:139], v[138:139]
	v_pk_mul_f32 v[132:133], v[132:133], v[132:133]
	v_pk_mul_f32 v[180:181], v[128:129], v[128:129]
	v_pk_mul_f32 v[134:135], v[134:135], v[134:135]
	v_pk_mul_f32 v[182:183], v[130:131], v[130:131]
	v_cvt_pk_bf16_f32 v128, v140, v141
	v_cvt_pk_bf16_f32 v129, v142, v143
	v_cvt_pk_bf16_f32 v130, v136, v137
	v_cvt_pk_bf16_f32 v131, v138, v139
	v_cvt_pk_bf16_f32 v132, v132, v133
	v_cvt_pk_bf16_f32 v133, v134, v135
	v_cvt_pk_bf16_f32 v134, v180, v181
	v_cvt_pk_bf16_f32 v135, v182, v183
	global_store_dwordx4 v[162:163], v[128:131], off
	global_store_dwordx4 v[162:163], v[132:135], off offset:256
	s_nop 1
	v_mov_b32_e32 v130, v230
	v_or_b32_e32 v128, 32, v164
	v_ashrrev_i32_e32 v129, 31, v128
	v_lshl_add_u64 v[132:133], v[128:129], 2, s[12:13]
	s_nop 0
	v_fmamk_f32 v130, v130, 0x3a800000, v174
	v_mul_f32_e32 v131, 0x4f800000, v130
	v_cmp_gt_f32_e32 vcc, s75, v130
	s_nop 1
	v_cndmask_b32_e32 v134, v130, v131, vcc
	v_sqrt_f32_e32 v135, v134
	v_lshlrev_b64 v[130:131], 13, v[176:177]
	v_lshl_add_u64 v[130:131], s[22:23], 0, v[130:131]
	v_lshl_add_u64 v[130:131], v[130:131], 0, v[166:167]
	v_add_u32_e32 v136, -1, v135
	v_add_u32_e32 v137, 1, v135
	v_fma_f32 v138, -v136, v135, v134
	v_fma_f32 v139, -v137, v135, v134
	v_cmp_ge_f32_e64 s[4:5], 0, v138
	s_nop 1
	v_cndmask_b32_e64 v135, v135, v136, s[4:5]
	v_cmp_lt_f32_e64 s[4:5], 0, v139
	s_nop 1
	v_cndmask_b32_e64 v135, v135, v137, s[4:5]
	v_mul_f32_e32 v136, 0x37800000, v135
	v_cndmask_b32_e32 v135, v135, v136, vcc
	v_cmp_class_f32_e32 vcc, v134, v175
	s_nop 1
	v_cndmask_b32_e32 v134, v135, v134, vcc
	v_div_scale_f32 v135, s[4:5], v134, v134, 1.0
	v_rcp_f32_e32 v136, v135
	v_div_scale_f32 v137, vcc, 1.0, v134, 1.0
	v_fma_f32 v138, -v135, v136, 1.0
	v_fmac_f32_e32 v136, v138, v136
	v_mul_f32_e32 v138, v137, v136
	v_fma_f32 v139, -v135, v138, v137
	v_fmac_f32_e32 v138, v139, v136
	v_fma_f32 v135, -v135, v138, v137
	v_div_fmas_f32 v135, v135, v136, v138
	v_div_fixup_f32 v134, v135, v134, 1.0
	v_pk_fma_f32 v[126:127], v[126:127], v[134:135], v[102:103] op_sel_hi:[1,0,1]
	v_pk_fma_f32 v[124:125], v[124:125], v[134:135], v[100:101] op_sel_hi:[1,0,1]
	v_pk_fma_f32 v[122:123], v[122:123], v[134:135], v[98:99] op_sel_hi:[1,0,1]
	v_pk_fma_f32 v[120:121], v[120:121], v[134:135], v[96:97] op_sel_hi:[1,0,1]
	v_pk_fma_f32 v[118:119], v[118:119], v[134:135], v[94:95] op_sel_hi:[1,0,1]
	v_pk_fma_f32 v[116:117], v[116:117], v[134:135], v[92:93] op_sel_hi:[1,0,1]
	v_pk_fma_f32 v[114:115], v[114:115], v[134:135], v[90:91] op_sel_hi:[1,0,1]
	v_pk_fma_f32 v[112:113], v[112:113], v[134:135], v[88:89] op_sel_hi:[1,0,1]
	v_max_f32_e32 v124, 0, v124
	v_max_f32_e32 v120, 0, v120
	v_max_f32_e32 v125, 0, v125
	v_max_f32_e32 v121, 0, v121
	v_max_f32_e32 v126, 0, v126
	v_max_f32_e32 v122, 0, v122
	v_max_f32_e32 v127, 0, v127
	v_max_f32_e32 v123, 0, v123
	v_max_f32_e32 v116, 0, v116
	v_max_f32_e32 v112, 0, v112
	v_max_f32_e32 v117, 0, v117
	v_max_f32_e32 v113, 0, v113
	v_max_f32_e32 v118, 0, v118
	v_max_f32_e32 v114, 0, v114
	v_max_f32_e32 v119, 0, v119
	v_max_f32_e32 v115, 0, v115
	v_pk_mul_f32 v[124:125], v[124:125], v[124:125]
	v_pk_mul_f32 v[120:121], v[120:121], v[120:121]
	v_pk_mul_f32 v[126:127], v[126:127], v[126:127]
	v_pk_mul_f32 v[122:123], v[122:123], v[122:123]
	v_pk_mul_f32 v[116:117], v[116:117], v[116:117]
	v_pk_mul_f32 v[134:135], v[112:113], v[112:113]
	v_pk_mul_f32 v[118:119], v[118:119], v[118:119]
	v_pk_mul_f32 v[136:137], v[114:115], v[114:115]
	v_cvt_pk_bf16_f32 v112, v124, v125
	v_cvt_pk_bf16_f32 v113, v126, v127
	v_cvt_pk_bf16_f32 v114, v120, v121
	v_cvt_pk_bf16_f32 v115, v122, v123
	v_cvt_pk_bf16_f32 v116, v116, v117
	v_cvt_pk_bf16_f32 v117, v118, v119
	v_cvt_pk_bf16_f32 v118, v134, v135
	v_cvt_pk_bf16_f32 v119, v136, v137
	global_store_dwordx4 v[130:131], v[112:115], off
	global_store_dwordx4 v[130:131], v[116:119], off offset:256
	s_nop 1
	v_mov_b32_e32 v114, v231
	v_or_b32_e32 v112, 48, v164
	v_ashrrev_i32_e32 v113, 31, v112
	v_lshl_add_u64 v[116:117], v[112:113], 2, s[12:13]
	s_nop 0
	v_fmamk_f32 v114, v114, 0x3a800000, v174
	v_mul_f32_e32 v115, 0x4f800000, v114
	v_cmp_gt_f32_e32 vcc, s75, v114
	s_nop 1
	v_cndmask_b32_e32 v118, v114, v115, vcc
	v_sqrt_f32_e32 v119, v118
	v_lshlrev_b64 v[114:115], 13, v[128:129]
	v_lshl_add_u64 v[114:115], s[22:23], 0, v[114:115]
	v_lshl_add_u64 v[114:115], v[114:115], 0, v[166:167]
	v_add_u32_e32 v120, -1, v119
	v_add_u32_e32 v121, 1, v119
	v_fma_f32 v122, -v120, v119, v118
	v_fma_f32 v123, -v121, v119, v118
	v_cmp_ge_f32_e64 s[4:5], 0, v122
	s_nop 1
	v_cndmask_b32_e64 v119, v119, v120, s[4:5]
	v_cmp_lt_f32_e64 s[4:5], 0, v123
	s_nop 1
	v_cndmask_b32_e64 v119, v119, v121, s[4:5]
	v_mul_f32_e32 v120, 0x37800000, v119
	v_cndmask_b32_e32 v119, v119, v120, vcc
	v_cmp_class_f32_e32 vcc, v118, v175
	s_nop 1
	v_cndmask_b32_e32 v118, v119, v118, vcc
	v_div_scale_f32 v119, s[4:5], v118, v118, 1.0
	v_rcp_f32_e32 v120, v119
	v_div_scale_f32 v121, vcc, 1.0, v118, 1.0
	v_fma_f32 v122, -v119, v120, 1.0
	v_fmac_f32_e32 v120, v122, v120
	v_mul_f32_e32 v122, v121, v120
	v_fma_f32 v123, -v119, v122, v121
	v_fmac_f32_e32 v122, v123, v120
	v_fma_f32 v119, -v119, v122, v121
	v_div_fmas_f32 v119, v119, v120, v122
	v_div_fixup_f32 v118, v119, v118, 1.0
	v_pk_fma_f32 v[110:111], v[110:111], v[118:119], v[102:103] op_sel_hi:[1,0,1]
	v_pk_fma_f32 v[108:109], v[108:109], v[118:119], v[100:101] op_sel_hi:[1,0,1]
	v_pk_fma_f32 v[106:107], v[106:107], v[118:119], v[98:99] op_sel_hi:[1,0,1]
	v_pk_fma_f32 v[104:105], v[104:105], v[118:119], v[96:97] op_sel_hi:[1,0,1]
	v_pk_fma_f32 v[86:87], v[86:87], v[118:119], v[94:95] op_sel_hi:[1,0,1]
	v_pk_fma_f32 v[84:85], v[84:85], v[118:119], v[92:93] op_sel_hi:[1,0,1]
	v_pk_fma_f32 v[82:83], v[82:83], v[118:119], v[90:91] op_sel_hi:[1,0,1]
	v_pk_fma_f32 v[80:81], v[80:81], v[118:119], v[88:89] op_sel_hi:[1,0,1]
	v_max_f32_e32 v108, 0, v108
	v_max_f32_e32 v104, 0, v104
	v_max_f32_e32 v109, 0, v109
	v_max_f32_e32 v105, 0, v105
	v_max_f32_e32 v110, 0, v110
	v_max_f32_e32 v106, 0, v106
	v_max_f32_e32 v111, 0, v111
	v_max_f32_e32 v107, 0, v107
	v_max_f32_e32 v84, 0, v84
	v_max_f32_e32 v80, 0, v80
	v_max_f32_e32 v85, 0, v85
	v_max_f32_e32 v81, 0, v81
	v_max_f32_e32 v86, 0, v86
	v_max_f32_e32 v82, 0, v82
	v_max_f32_e32 v87, 0, v87
	v_max_f32_e32 v83, 0, v83
	v_pk_mul_f32 v[108:109], v[108:109], v[108:109]
	v_pk_mul_f32 v[104:105], v[104:105], v[104:105]
	v_pk_mul_f32 v[110:111], v[110:111], v[110:111]
	v_pk_mul_f32 v[106:107], v[106:107], v[106:107]
	v_pk_mul_f32 v[84:85], v[84:85], v[84:85]
	v_pk_mul_f32 v[118:119], v[80:81], v[80:81]
	v_pk_mul_f32 v[86:87], v[86:87], v[86:87]
	v_pk_mul_f32 v[120:121], v[82:83], v[82:83]
	v_cvt_pk_bf16_f32 v80, v108, v109
	v_cvt_pk_bf16_f32 v81, v110, v111
	v_cvt_pk_bf16_f32 v82, v104, v105
	v_cvt_pk_bf16_f32 v83, v106, v107
	v_cvt_pk_bf16_f32 v84, v84, v85
	v_cvt_pk_bf16_f32 v85, v86, v87
	v_cvt_pk_bf16_f32 v86, v118, v119
	v_cvt_pk_bf16_f32 v87, v120, v121
	global_store_dwordx4 v[114:115], v[80:83], off
	global_store_dwordx4 v[114:115], v[84:87], off offset:256
	s_nop 1
	v_mov_b32_e32 v80, v232
	s_nop 0
	v_fmamk_f32 v80, v80, 0x3a800000, v174
	v_mul_f32_e32 v81, 0x4f800000, v80
	v_cmp_gt_f32_e32 vcc, s75, v80
	s_nop 1
	v_cndmask_b32_e32 v82, v80, v81, vcc
	v_sqrt_f32_e32 v83, v82
	v_lshlrev_b64 v[80:81], 13, v[112:113]
	v_lshl_add_u64 v[80:81], s[22:23], 0, v[80:81]
	v_lshl_add_u64 v[80:81], v[80:81], 0, v[166:167]
	v_add_u32_e32 v84, -1, v83
	v_add_u32_e32 v85, 1, v83
	v_fma_f32 v86, -v84, v83, v82
	v_fma_f32 v87, -v85, v83, v82
	v_cmp_ge_f32_e64 s[4:5], 0, v86
	s_nop 1
	v_cndmask_b32_e64 v83, v83, v84, s[4:5]
	v_cmp_lt_f32_e64 s[4:5], 0, v87
	s_nop 1
	v_cndmask_b32_e64 v83, v83, v85, s[4:5]
	v_mul_f32_e32 v84, 0x37800000, v83
	v_cndmask_b32_e32 v83, v83, v84, vcc
	v_cmp_class_f32_e32 vcc, v82, v175
	s_nop 1
	v_cndmask_b32_e32 v82, v83, v82, vcc
	v_div_scale_f32 v83, s[4:5], v82, v82, 1.0
	v_rcp_f32_e32 v84, v83
	v_div_scale_f32 v85, vcc, 1.0, v82, 1.0
	v_fma_f32 v86, -v83, v84, 1.0
	v_fmac_f32_e32 v84, v86, v84
	v_mul_f32_e32 v86, v85, v84
	v_fma_f32 v87, -v83, v86, v85
	v_fmac_f32_e32 v86, v87, v84
	v_fma_f32 v83, -v83, v86, v85
	v_div_fmas_f32 v83, v83, v84, v86
	v_div_fixup_f32 v82, v83, v82, 1.0
	v_pk_fma_f32 v[78:79], v[78:79], v[82:83], v[102:103] op_sel_hi:[1,0,1]
	v_pk_fma_f32 v[76:77], v[76:77], v[82:83], v[100:101] op_sel_hi:[1,0,1]
	v_pk_fma_f32 v[74:75], v[74:75], v[82:83], v[98:99] op_sel_hi:[1,0,1]
	v_pk_fma_f32 v[72:73], v[72:73], v[82:83], v[96:97] op_sel_hi:[1,0,1]
	v_pk_fma_f32 v[70:71], v[70:71], v[82:83], v[94:95] op_sel_hi:[1,0,1]
	v_pk_fma_f32 v[68:69], v[68:69], v[82:83], v[92:93] op_sel_hi:[1,0,1]
	v_pk_fma_f32 v[66:67], v[66:67], v[82:83], v[90:91] op_sel_hi:[1,0,1]
	v_pk_fma_f32 v[64:65], v[64:65], v[82:83], v[88:89] op_sel_hi:[1,0,1]
	v_max_f32_e32 v76, 0, v76
	v_max_f32_e32 v72, 0, v72
	v_max_f32_e32 v77, 0, v77
	v_max_f32_e32 v73, 0, v73
	v_max_f32_e32 v78, 0, v78
	v_max_f32_e32 v74, 0, v74
	v_max_f32_e32 v79, 0, v79
	v_max_f32_e32 v75, 0, v75
	v_max_f32_e32 v68, 0, v68
	v_max_f32_e32 v64, 0, v64
	v_max_f32_e32 v69, 0, v69
	v_max_f32_e32 v65, 0, v65
	v_max_f32_e32 v70, 0, v70
	v_max_f32_e32 v66, 0, v66
	v_max_f32_e32 v71, 0, v71
	v_max_f32_e32 v67, 0, v67
	v_pk_mul_f32 v[76:77], v[76:77], v[76:77]
	v_pk_mul_f32 v[72:73], v[72:73], v[72:73]
	v_pk_mul_f32 v[78:79], v[78:79], v[78:79]
	v_pk_mul_f32 v[74:75], v[74:75], v[74:75]
	v_pk_mul_f32 v[68:69], v[68:69], v[68:69]
	v_pk_mul_f32 v[82:83], v[64:65], v[64:65]
	v_pk_mul_f32 v[70:71], v[70:71], v[70:71]
	v_pk_mul_f32 v[84:85], v[66:67], v[66:67]
	v_cvt_pk_bf16_f32 v64, v76, v77
	v_cvt_pk_bf16_f32 v65, v78, v79
	v_cvt_pk_bf16_f32 v66, v72, v73
	v_cvt_pk_bf16_f32 v67, v74, v75
	v_cvt_pk_bf16_f32 v68, v68, v69
	v_cvt_pk_bf16_f32 v69, v70, v71
	v_cvt_pk_bf16_f32 v70, v82, v83
	v_cvt_pk_bf16_f32 v71, v84, v85
	global_store_dwordx4 v[80:81], v[64:67], off
	global_store_dwordx4 v[80:81], v[68:71], off offset:256
	s_nop 1
	v_mov_b32_e32 v64, v233
	s_nop 0
	v_fmamk_f32 v64, v64, 0x3a800000, v174
	v_mul_f32_e32 v65, 0x4f800000, v64
	v_cmp_gt_f32_e32 vcc, s75, v64
	s_nop 1
	v_cndmask_b32_e32 v66, v64, v65, vcc
	v_sqrt_f32_e32 v67, v66
	v_lshl_add_u64 v[64:65], v[162:163], 0, s[20:21]
	v_add_u32_e32 v68, -1, v67
	v_add_u32_e32 v69, 1, v67
	v_fma_f32 v70, -v68, v67, v66
	v_fma_f32 v71, -v69, v67, v66
	v_cmp_ge_f32_e64 s[4:5], 0, v70
	s_nop 1
	v_cndmask_b32_e64 v67, v67, v68, s[4:5]
	v_cmp_lt_f32_e64 s[4:5], 0, v71
	s_nop 1
	v_cndmask_b32_e64 v67, v67, v69, s[4:5]
	v_mul_f32_e32 v68, 0x37800000, v67
	v_cndmask_b32_e32 v67, v67, v68, vcc
	v_cmp_class_f32_e32 vcc, v66, v175
	s_nop 1
	v_cndmask_b32_e32 v68, v67, v66, vcc
	v_div_scale_f32 v69, s[4:5], v68, v68, 1.0
	v_rcp_f32_e32 v70, v69
	v_add_co_u32_e32 v66, vcc, s76, v162
	v_fma_f32 v72, -v69, v70, 1.0
	s_nop 0
	v_addc_co_u32_e32 v67, vcc, 0, v163, vcc
	v_div_scale_f32 v71, vcc, 1.0, v68, 1.0
	v_fmac_f32_e32 v70, v72, v70
	v_mul_f32_e32 v72, v71, v70
	v_fma_f32 v73, -v69, v72, v71
	v_fmac_f32_e32 v72, v73, v70
	v_fma_f32 v69, -v69, v72, v71
	v_div_fmas_f32 v69, v69, v70, v72
	v_div_fixup_f32 v68, v69, v68, 1.0
	v_pk_fma_f32 v[62:63], v[62:63], v[68:69], v[102:103] op_sel_hi:[1,0,1]
	v_pk_fma_f32 v[60:61], v[60:61], v[68:69], v[100:101] op_sel_hi:[1,0,1]
	v_pk_fma_f32 v[58:59], v[58:59], v[68:69], v[98:99] op_sel_hi:[1,0,1]
	v_pk_fma_f32 v[56:57], v[56:57], v[68:69], v[96:97] op_sel_hi:[1,0,1]
	v_pk_fma_f32 v[54:55], v[54:55], v[68:69], v[94:95] op_sel_hi:[1,0,1]
	v_pk_fma_f32 v[52:53], v[52:53], v[68:69], v[92:93] op_sel_hi:[1,0,1]
	v_pk_fma_f32 v[50:51], v[50:51], v[68:69], v[90:91] op_sel_hi:[1,0,1]
	v_pk_fma_f32 v[48:49], v[48:49], v[68:69], v[88:89] op_sel_hi:[1,0,1]
	v_max_f32_e32 v60, 0, v60
	v_max_f32_e32 v56, 0, v56
	v_max_f32_e32 v61, 0, v61
	v_max_f32_e32 v57, 0, v57
	v_max_f32_e32 v62, 0, v62
	v_max_f32_e32 v58, 0, v58
	v_max_f32_e32 v63, 0, v63
	v_max_f32_e32 v59, 0, v59
	v_max_f32_e32 v52, 0, v52
	v_max_f32_e32 v48, 0, v48
	v_max_f32_e32 v53, 0, v53
	v_max_f32_e32 v49, 0, v49
	v_max_f32_e32 v54, 0, v54
	v_max_f32_e32 v50, 0, v50
	v_max_f32_e32 v55, 0, v55
	v_max_f32_e32 v51, 0, v51
	v_pk_mul_f32 v[60:61], v[60:61], v[60:61]
	v_pk_mul_f32 v[56:57], v[56:57], v[56:57]
	v_pk_mul_f32 v[62:63], v[62:63], v[62:63]
	v_pk_mul_f32 v[58:59], v[58:59], v[58:59]
	v_pk_mul_f32 v[52:53], v[52:53], v[52:53]
	v_pk_mul_f32 v[68:69], v[48:49], v[48:49]
	v_pk_mul_f32 v[54:55], v[54:55], v[54:55]
	v_pk_mul_f32 v[70:71], v[50:51], v[50:51]
	v_cvt_pk_bf16_f32 v48, v60, v61
	v_cvt_pk_bf16_f32 v49, v62, v63
	v_cvt_pk_bf16_f32 v50, v56, v57
	v_cvt_pk_bf16_f32 v51, v58, v59
	v_cvt_pk_bf16_f32 v52, v52, v53
	v_cvt_pk_bf16_f32 v53, v54, v55
	v_cvt_pk_bf16_f32 v54, v68, v69
	v_cvt_pk_bf16_f32 v55, v70, v71
	global_store_dwordx4 v[66:67], v[48:51], off
	global_store_dwordx4 v[64:65], v[52:55], off offset:256
	s_nop 1
	v_mov_b32_e32 v48, v234
	s_nop 0
	v_fmamk_f32 v48, v48, 0x3a800000, v174
	v_mul_f32_e32 v49, 0x4f800000, v48
	v_cmp_gt_f32_e32 vcc, s75, v48
	s_nop 1
	v_cndmask_b32_e32 v50, v48, v49, vcc
	v_sqrt_f32_e32 v51, v50
	v_lshl_add_u64 v[48:49], v[162:163], 0, s[24:25]
	v_add_u32_e32 v52, -1, v51
	v_add_u32_e32 v53, 1, v51
	v_fma_f32 v54, -v52, v51, v50
	v_fma_f32 v55, -v53, v51, v50
	v_cmp_ge_f32_e64 s[4:5], 0, v54
	s_nop 1
	v_cndmask_b32_e64 v51, v51, v52, s[4:5]
	v_cmp_lt_f32_e64 s[4:5], 0, v55
	s_nop 1
	v_cndmask_b32_e64 v51, v51, v53, s[4:5]
	v_mul_f32_e32 v52, 0x37800000, v51
	v_cndmask_b32_e32 v51, v51, v52, vcc
	v_cmp_class_f32_e32 vcc, v50, v175
	s_nop 1
	v_cndmask_b32_e32 v52, v51, v50, vcc
	v_div_scale_f32 v53, s[4:5], v52, v52, 1.0
	v_rcp_f32_e32 v54, v53
	v_add_co_u32_e32 v50, vcc, s77, v162
	v_fma_f32 v56, -v53, v54, 1.0
	s_nop 0
	v_addc_co_u32_e32 v51, vcc, 0, v163, vcc
	v_div_scale_f32 v55, vcc, 1.0, v52, 1.0
	v_fmac_f32_e32 v54, v56, v54
	v_mul_f32_e32 v56, v55, v54
	v_fma_f32 v57, -v53, v56, v55
	v_fmac_f32_e32 v56, v57, v54
	v_fma_f32 v53, -v53, v56, v55
	v_div_fmas_f32 v53, v53, v54, v56
	v_div_fixup_f32 v52, v53, v52, 1.0
	v_pk_fma_f32 v[46:47], v[46:47], v[52:53], v[102:103] op_sel_hi:[1,0,1]
	v_pk_fma_f32 v[44:45], v[44:45], v[52:53], v[100:101] op_sel_hi:[1,0,1]
	v_pk_fma_f32 v[42:43], v[42:43], v[52:53], v[98:99] op_sel_hi:[1,0,1]
	v_pk_fma_f32 v[40:41], v[40:41], v[52:53], v[96:97] op_sel_hi:[1,0,1]
	v_pk_fma_f32 v[38:39], v[38:39], v[52:53], v[94:95] op_sel_hi:[1,0,1]
	v_pk_fma_f32 v[36:37], v[36:37], v[52:53], v[92:93] op_sel_hi:[1,0,1]
	v_pk_fma_f32 v[34:35], v[34:35], v[52:53], v[90:91] op_sel_hi:[1,0,1]
	v_pk_fma_f32 v[32:33], v[32:33], v[52:53], v[88:89] op_sel_hi:[1,0,1]
	v_max_f32_e32 v44, 0, v44
	v_max_f32_e32 v40, 0, v40
	v_max_f32_e32 v45, 0, v45
	v_max_f32_e32 v41, 0, v41
	v_max_f32_e32 v46, 0, v46
	v_max_f32_e32 v42, 0, v42
	v_max_f32_e32 v47, 0, v47
	v_max_f32_e32 v43, 0, v43
	v_max_f32_e32 v36, 0, v36
	v_max_f32_e32 v32, 0, v32
	v_max_f32_e32 v37, 0, v37
	v_max_f32_e32 v33, 0, v33
	v_max_f32_e32 v38, 0, v38
	v_max_f32_e32 v34, 0, v34
	v_max_f32_e32 v39, 0, v39
	v_max_f32_e32 v35, 0, v35
	v_pk_mul_f32 v[44:45], v[44:45], v[44:45]
	v_pk_mul_f32 v[40:41], v[40:41], v[40:41]
	v_pk_mul_f32 v[46:47], v[46:47], v[46:47]
	v_pk_mul_f32 v[42:43], v[42:43], v[42:43]
	v_pk_mul_f32 v[36:37], v[36:37], v[36:37]
	v_pk_mul_f32 v[52:53], v[32:33], v[32:33]
	v_pk_mul_f32 v[38:39], v[38:39], v[38:39]
	v_pk_mul_f32 v[54:55], v[34:35], v[34:35]
	v_cvt_pk_bf16_f32 v32, v44, v45
	v_cvt_pk_bf16_f32 v33, v46, v47
	v_cvt_pk_bf16_f32 v34, v40, v41
	v_cvt_pk_bf16_f32 v35, v42, v43
	v_cvt_pk_bf16_f32 v36, v36, v37
	v_cvt_pk_bf16_f32 v37, v38, v39
	v_cvt_pk_bf16_f32 v38, v52, v53
	v_cvt_pk_bf16_f32 v39, v54, v55
	global_store_dwordx4 v[50:51], v[32:35], off
	global_store_dwordx4 v[48:49], v[36:39], off offset:256
	s_nop 1
	v_mov_b32_e32 v32, v235
	s_nop 0
	v_fmamk_f32 v32, v32, 0x3a800000, v174
	v_mul_f32_e32 v33, 0x4f800000, v32
	v_cmp_gt_f32_e32 vcc, s75, v32
	s_nop 1
	v_cndmask_b32_e32 v34, v32, v33, vcc
	v_sqrt_f32_e32 v35, v34
	v_lshl_add_u64 v[32:33], v[162:163], 0, s[26:27]
	v_add_u32_e32 v36, -1, v35
	v_add_u32_e32 v37, 1, v35
	v_fma_f32 v38, -v36, v35, v34
	v_fma_f32 v39, -v37, v35, v34
	v_cmp_ge_f32_e64 s[4:5], 0, v38
	s_nop 1
	v_cndmask_b32_e64 v35, v35, v36, s[4:5]
	v_cmp_lt_f32_e64 s[4:5], 0, v39
	s_nop 1
	v_cndmask_b32_e64 v35, v35, v37, s[4:5]
	v_mul_f32_e32 v36, 0x37800000, v35
	v_cndmask_b32_e32 v35, v35, v36, vcc
	v_cmp_class_f32_e32 vcc, v34, v175
	s_nop 1
	v_cndmask_b32_e32 v36, v35, v34, vcc
	v_div_scale_f32 v37, s[4:5], v36, v36, 1.0
	v_rcp_f32_e32 v38, v37
	v_add_co_u32_e32 v34, vcc, s78, v162
	v_fma_f32 v40, -v37, v38, 1.0
	s_nop 0
	v_addc_co_u32_e32 v35, vcc, 0, v163, vcc
	v_div_scale_f32 v39, vcc, 1.0, v36, 1.0
	v_fmac_f32_e32 v38, v40, v38
	v_mul_f32_e32 v40, v39, v38
	v_fma_f32 v41, -v37, v40, v39
	v_fmac_f32_e32 v40, v41, v38
	v_fma_f32 v37, -v37, v40, v39
	v_div_fmas_f32 v37, v37, v38, v40
	v_div_fixup_f32 v36, v37, v36, 1.0
	v_pk_fma_f32 v[30:31], v[30:31], v[36:37], v[102:103] op_sel_hi:[1,0,1]
	v_pk_fma_f32 v[28:29], v[28:29], v[36:37], v[100:101] op_sel_hi:[1,0,1]
	v_pk_fma_f32 v[26:27], v[26:27], v[36:37], v[98:99] op_sel_hi:[1,0,1]
	v_pk_fma_f32 v[24:25], v[24:25], v[36:37], v[96:97] op_sel_hi:[1,0,1]
	v_pk_fma_f32 v[22:23], v[22:23], v[36:37], v[94:95] op_sel_hi:[1,0,1]
	v_pk_fma_f32 v[20:21], v[20:21], v[36:37], v[92:93] op_sel_hi:[1,0,1]
	v_pk_fma_f32 v[18:19], v[18:19], v[36:37], v[90:91] op_sel_hi:[1,0,1]
	v_pk_fma_f32 v[16:17], v[16:17], v[36:37], v[88:89] op_sel_hi:[1,0,1]
	v_max_f32_e32 v28, 0, v28
	v_max_f32_e32 v24, 0, v24
	v_max_f32_e32 v29, 0, v29
	v_max_f32_e32 v25, 0, v25
	v_max_f32_e32 v30, 0, v30
	v_max_f32_e32 v26, 0, v26
	v_max_f32_e32 v31, 0, v31
	v_max_f32_e32 v27, 0, v27
	v_max_f32_e32 v20, 0, v20
	v_max_f32_e32 v16, 0, v16
	v_max_f32_e32 v21, 0, v21
	v_max_f32_e32 v17, 0, v17
	v_max_f32_e32 v22, 0, v22
	v_max_f32_e32 v18, 0, v18
	v_max_f32_e32 v23, 0, v23
	v_max_f32_e32 v19, 0, v19
	v_pk_mul_f32 v[28:29], v[28:29], v[28:29]
	v_pk_mul_f32 v[24:25], v[24:25], v[24:25]
	v_pk_mul_f32 v[30:31], v[30:31], v[30:31]
	v_pk_mul_f32 v[26:27], v[26:27], v[26:27]
	v_pk_mul_f32 v[20:21], v[20:21], v[20:21]
	v_pk_mul_f32 v[36:37], v[16:17], v[16:17]
	v_pk_mul_f32 v[22:23], v[22:23], v[22:23]
	v_pk_mul_f32 v[38:39], v[18:19], v[18:19]
	v_cvt_pk_bf16_f32 v16, v28, v29
	v_cvt_pk_bf16_f32 v17, v30, v31
	v_cvt_pk_bf16_f32 v18, v24, v25
	v_cvt_pk_bf16_f32 v19, v26, v27
	v_cvt_pk_bf16_f32 v20, v20, v21
	v_cvt_pk_bf16_f32 v21, v22, v23
	v_cvt_pk_bf16_f32 v22, v36, v37
	v_cvt_pk_bf16_f32 v23, v38, v39
	global_store_dwordx4 v[34:35], v[16:19], off
	global_store_dwordx4 v[32:33], v[20:23], off offset:256
	s_nop 1
	v_mov_b32_e32 v16, v236
	s_nop 0
	v_fmamk_f32 v16, v16, 0x3a800000, v174
	v_mul_f32_e32 v17, 0x4f800000, v16
	v_cmp_gt_f32_e32 vcc, s75, v16
	s_nop 1
	v_cndmask_b32_e32 v18, v16, v17, vcc
	v_sqrt_f32_e32 v19, v18
	v_lshl_add_u64 v[16:17], v[162:163], 0, s[28:29]
	v_add_u32_e32 v20, -1, v19
	v_add_u32_e32 v21, 1, v19
	v_fma_f32 v22, -v20, v19, v18
	v_fma_f32 v23, -v21, v19, v18
	v_cmp_ge_f32_e64 s[4:5], 0, v22
	s_nop 1
	v_cndmask_b32_e64 v19, v19, v20, s[4:5]
	v_cmp_lt_f32_e64 s[4:5], 0, v23
	s_nop 1
	v_cndmask_b32_e64 v19, v19, v21, s[4:5]
	v_mul_f32_e32 v20, 0x37800000, v19
	v_cndmask_b32_e32 v19, v19, v20, vcc
	v_cmp_class_f32_e32 vcc, v18, v175
	s_nop 1
	v_cndmask_b32_e32 v20, v19, v18, vcc
	v_div_scale_f32 v21, s[4:5], v20, v20, 1.0
	v_rcp_f32_e32 v22, v21
	v_add_co_u32_e32 v18, vcc, s79, v162
	v_fma_f32 v24, -v21, v22, 1.0
	s_nop 0
	v_addc_co_u32_e32 v19, vcc, 0, v163, vcc
	v_div_scale_f32 v23, vcc, 1.0, v20, 1.0
	v_fmac_f32_e32 v22, v24, v22
	v_mul_f32_e32 v24, v23, v22
	v_fma_f32 v25, -v21, v24, v23
	v_fmac_f32_e32 v24, v25, v22
	v_fma_f32 v21, -v21, v24, v23
	v_div_fmas_f32 v21, v21, v22, v24
	v_div_fixup_f32 v20, v21, v20, 1.0
	v_pk_fma_f32 v[14:15], v[14:15], v[20:21], v[102:103] op_sel_hi:[1,0,1]
	v_pk_fma_f32 v[12:13], v[12:13], v[20:21], v[100:101] op_sel_hi:[1,0,1]
	v_pk_fma_f32 v[10:11], v[10:11], v[20:21], v[98:99] op_sel_hi:[1,0,1]
	v_pk_fma_f32 v[8:9], v[8:9], v[20:21], v[96:97] op_sel_hi:[1,0,1]
	v_pk_fma_f32 v[6:7], v[6:7], v[20:21], v[94:95] op_sel_hi:[1,0,1]
	v_pk_fma_f32 v[4:5], v[4:5], v[20:21], v[92:93] op_sel_hi:[1,0,1]
	v_pk_fma_f32 v[2:3], v[2:3], v[20:21], v[90:91] op_sel_hi:[1,0,1]
	v_pk_fma_f32 v[0:1], v[0:1], v[20:21], v[88:89] op_sel_hi:[1,0,1]
	v_max_f32_e32 v12, 0, v12
	v_max_f32_e32 v8, 0, v8
	v_max_f32_e32 v13, 0, v13
	v_max_f32_e32 v9, 0, v9
	v_max_f32_e32 v14, 0, v14
	v_max_f32_e32 v10, 0, v10
	v_max_f32_e32 v15, 0, v15
	v_max_f32_e32 v11, 0, v11
	v_max_f32_e32 v4, 0, v4
	v_max_f32_e32 v0, 0, v0
	v_max_f32_e32 v5, 0, v5
	v_max_f32_e32 v1, 0, v1
	v_max_f32_e32 v6, 0, v6
	v_max_f32_e32 v2, 0, v2
	v_max_f32_e32 v7, 0, v7
	v_max_f32_e32 v3, 0, v3
	v_pk_mul_f32 v[12:13], v[12:13], v[12:13]
	v_pk_mul_f32 v[8:9], v[8:9], v[8:9]
	v_pk_mul_f32 v[14:15], v[14:15], v[14:15]
	v_pk_mul_f32 v[10:11], v[10:11], v[10:11]
	s_andn2_b64 vcc, exec, s[0:1]
	v_pk_mul_f32 v[4:5], v[4:5], v[4:5]
	v_pk_mul_f32 v[20:21], v[0:1], v[0:1]
	v_pk_mul_f32 v[6:7], v[6:7], v[6:7]
	v_pk_mul_f32 v[22:23], v[2:3], v[2:3]
	v_cvt_pk_bf16_f32 v0, v12, v13
	v_cvt_pk_bf16_f32 v1, v14, v15
	v_cvt_pk_bf16_f32 v2, v8, v9
	v_cvt_pk_bf16_f32 v3, v10, v11
	s_mov_b64 s[0:1], -1
	v_cvt_pk_bf16_f32 v4, v4, v5
	v_cvt_pk_bf16_f32 v5, v6, v7
	v_cvt_pk_bf16_f32 v6, v20, v21
	v_cvt_pk_bf16_f32 v7, v22, v23
	global_store_dwordx4 v[18:19], v[0:3], off
	global_store_dwordx4 v[16:17], v[4:7], off offset:256
	s_cbranch_vccnz .LBB0_745
	s_andn2_b64 vcc, exec, s[8:9]
	s_cbranch_vccnz .LBB0_744
	s_barrier
	s_branch .LBB0_744
